# GEMM tile headers: accumulator clear by eight zero-operand 32x32x16 MFMAs (C = inline 0) instead of 128 v_mov_b32 per tile
# speedup vs baseline: 1.0154x; 1.0074x over previous
.LBB0_139:
	s_ashr_i32 s23, s22, 31
	s_lshl_b64 s[24:25], s[22:23], 19
	s_add_u32 s24, s80, s24
	s_addc_u32 s25, s81, s25
	s_and_b64 s[30:31], s[42:43], exec
	s_cselect_b32 s23, s25, s41
	s_cselect_b32 s35, s24, s40
	s_ashr_i32 s21, s20, 31
	s_lshl_b64 s[30:31], s[20:21], 19
	s_add_u32 s30, s6, s30
	s_addc_u32 s31, s7, s31
	s_and_b64 s[46:47], s[42:43], exec
	s_cselect_b32 s21, s31, s45
	s_cselect_b32 s36, s30, s44
	s_add_u32 s40, s40, 0x40080
	s_addc_u32 s41, s41, 0
	s_add_u32 s48, s44, 0x100
	v_mov_b32_e32 v228, 0
	v_mov_b32_e32 v229, 0
	v_mov_b32_e32 v230, 0
	v_mov_b32_e32 v231, 0
	s_addc_u32 s49, s45, 0
	s_mov_b32 s50, -2
	v_mfma_f32_32x32x16_bf16 v[0:15], v[228:231], v[228:231], 0
	v_mfma_f32_32x32x16_bf16 v[16:31], v[228:231], v[228:231], 0
	v_mfma_f32_32x32x16_bf16 v[32:47], v[228:231], v[228:231], 0
	v_mfma_f32_32x32x16_bf16 v[48:63], v[228:231], v[228:231], 0
	v_mfma_f32_32x32x16_bf16 v[64:79], v[228:231], v[228:231], 0
	v_mfma_f32_32x32x16_bf16 v[80:95], v[228:231], v[228:231], 0
	v_mfma_f32_32x32x16_bf16 v[96:111], v[228:231], v[228:231], 0
	v_mfma_f32_32x32x16_bf16 v[112:127], v[228:231], v[228:231], 0

.LBB0_415:
	s_add_u32 s50, s54, 0x80
	s_addc_u32 s51, s55, 0
	s_add_u32 s54, s52, 0x100
	v_mov_b32_e32 v228, 0
	v_mov_b32_e32 v229, 0
	v_mov_b32_e32 v230, 0
	v_mov_b32_e32 v231, 0
	s_addc_u32 s55, s53, 0
	s_mov_b32 s52, 0
	v_mfma_f32_32x32x16_bf16 v[0:15], v[228:231], v[228:231], 0
	v_mfma_f32_32x32x16_bf16 v[16:31], v[228:231], v[228:231], 0
	v_mfma_f32_32x32x16_bf16 v[32:47], v[228:231], v[228:231], 0
	v_mfma_f32_32x32x16_bf16 v[48:63], v[228:231], v[228:231], 0
	v_mfma_f32_32x32x16_bf16 v[64:79], v[228:231], v[228:231], 0
	v_mfma_f32_32x32x16_bf16 v[80:95], v[228:231], v[228:231], 0
	v_mfma_f32_32x32x16_bf16 v[96:111], v[228:231], v[228:231], 0
	v_mfma_f32_32x32x16_bf16 v[112:127], v[228:231], v[228:231], 0

.LBB0_854:
	s_add_u32 s34, s34, 0x80
	s_addc_u32 s35, s35, 0
	s_add_u32 s46, s46, 0x100
	v_mov_b32_e32 v228, 0
	v_mov_b32_e32 v229, 0
	v_mov_b32_e32 v230, 0
	v_mov_b32_e32 v231, 0
	s_addc_u32 s47, s47, 0
	s_mov_b32 s44, 0
	s_waitcnt lgkmcnt(0)
	v_mfma_f32_32x32x16_bf16 v[0:15], v[228:231], v[228:231], 0
	v_mfma_f32_32x32x16_bf16 v[16:31], v[228:231], v[228:231], 0
	v_mfma_f32_32x32x16_bf16 v[32:47], v[228:231], v[228:231], 0
	v_mfma_f32_32x32x16_bf16 v[48:63], v[228:231], v[228:231], 0
	v_mfma_f32_32x32x16_bf16 v[64:79], v[228:231], v[228:231], 0
	v_mfma_f32_32x32x16_bf16 v[80:95], v[228:231], v[228:231], 0
	v_mfma_f32_32x32x16_bf16 v[96:111], v[228:231], v[228:231], 0
	v_mfma_f32_32x32x16_bf16 v[112:127], v[228:231], v[228:231], 0
